# v36 + nt on P7's read-once sc_b row load (the row is overwritten in place by y_a)
# speedup vs baseline: 1.0027x; 1.0023x over previous
.Lya_rows:
	global_load_dwordx4 v[32:35], v3, s[46:47]
	global_load_dwordx4 v[36:39], v3, s[48:49] nt
	s_cmp_eq_u32 s40, 0
	s_cbranch_scc0 .Lya_l1n
	s_lshl_b32 s33, s7, 11
	s_add_u32 s42, s64, s33
	s_addc_u32 s43, s65, 0
	global_load_dwordx4 v[40:43], v3, s[42:43]
	s_branch .Lya_l0
